# dt job (critical barrier-2 shadow): all 24 operand fragment loads issued in one round instead of seven dependent rounds, 32 MFMAs behind four counted waits, row-scale loads batched; on top of v52
# baseline (speedup 1.0000x reference)
;     __device__ __forceinline__ int lane_() const { return hw_lane(); }
; __device__ __forceinline__ void p1b_dt(Frame& F, const Ptrs& P) {
;     ...
;     for (int c = blockIdx.x; c < M / 64; c += F.G) {
;         const int blk = F.G == 256 ? (8 * (c & 7) + ((c >> 3) & 7)) * 4 + (c >> 6) : c;
;         const bf16* ap = XB + (size_t)(blk * 64 + fr) * DM + 8 * fq + 128 * w; const bf16* bp = WIN + (size_t)(NMAIN + fr) * DM + 8 * fq + 128 * w;
;         bf16x8 a[4][4], b[2][4];
; #pragma unroll
;         for (int r = 0; r < 4; ++r)
; #pragma unroll
;             for (int ks = 0; ks < 4; ++ks) a[r][ks] = *(const bf16x8*)(ap + (size_t)(r * 16) * DM + 32 * ks);
; #pragma unroll
;         for (int q = 0; q < 2; ++q)
; #pragma unroll
;             for (int ks = 0; ks < 4; ++ks) b[q][ks] = *(const bf16x8*)(bp + (size_t)(q * 16) * DM + 32 * ks);
; #pragma unroll
;         for (int r = 0; r < 4; ++r)
; #pragma unroll
;             for (int q = 0; q < 2; ++q) { f32x4 acc = (f32x4){0.f, 0.f, 0.f, 0.f};
; #pragma unroll
;                 for (int ks = 0; ks < 4; ++ks) acc = __builtin_amdgcn_mfma_f32_16x16x32_bf16(a[r][ks], b[q][ks], acc, 0, 0, 0);
;                 part[(w * 8 + r * 2 + q) * 64 + lane_] = acc; }
.LBB0_376:
	s_lshl_b32 s9, s8, 6
	v_or_b32_e32 v0, s9, v56
	v_ashrrev_i32_e32 v1, 31, v0
	v_lshlrev_b64 v[0:1], 11, v[0:1]
	v_lshl_add_u64 v[86:87], v[32:33], 0, v[0:1]
	global_load_dwordx4 v[174:177], v[36:37], off
	global_load_dwordx4 v[190:193], v[40:41], off
	global_load_dwordx4 v[178:181], v[36:37], off offset:64
	global_load_dwordx4 v[194:197], v[42:43], off
	global_load_dwordx4 v[182:185], v[36:37], off offset:128
	global_load_dwordx4 v[198:201], v[44:45], off
	global_load_dwordx4 v[186:189], v[36:37], off offset:192
	global_load_dwordx4 v[202:205], v[46:47], off
	global_load_dwordx4 v[110:113], v[86:87], off
	global_load_dwordx4 v[114:117], v[86:87], off offset:64
	global_load_dwordx4 v[118:121], v[86:87], off offset:128
	global_load_dwordx4 v[122:125], v[86:87], off offset:192
	v_add_co_u32_e32 v98, vcc, 0x8000, v86
	s_nop 1
	v_addc_co_u32_e32 v99, vcc, 0, v87, vcc
	global_load_dwordx4 v[126:129], v[98:99], off
	global_load_dwordx4 v[130:133], v[98:99], off offset:64
	global_load_dwordx4 v[134:137], v[98:99], off offset:128
	global_load_dwordx4 v[138:141], v[98:99], off offset:192
	v_add_co_u32_e32 v102, vcc, 0x10000, v86
	s_nop 1
	v_addc_co_u32_e32 v103, vcc, 0, v87, vcc
	global_load_dwordx4 v[142:145], v[102:103], off
	global_load_dwordx4 v[146:149], v[102:103], off offset:64
	global_load_dwordx4 v[150:153], v[102:103], off offset:128
	global_load_dwordx4 v[154:157], v[102:103], off offset:192
	v_add_co_u32_e32 v104, vcc, 0x18000, v86
	s_nop 1
	v_addc_co_u32_e32 v105, vcc, 0, v87, vcc
	global_load_dwordx4 v[158:161], v[104:105], off
	global_load_dwordx4 v[162:165], v[104:105], off offset:64
	global_load_dwordx4 v[166:169], v[104:105], off offset:128
	global_load_dwordx4 v[170:173], v[104:105], off offset:192
	s_waitcnt vmcnt(12)
	v_mfma_f32_16x16x32_bf16 v[208:211], v[110:113], v[174:177], 0
	v_mfma_f32_16x16x32_bf16 v[212:215], v[110:113], v[190:193], 0
	v_mfma_f32_16x16x32_bf16 v[208:211], v[114:117], v[178:181], v[208:211]
	v_mfma_f32_16x16x32_bf16 v[212:215], v[114:117], v[194:197], v[212:215]
	v_mfma_f32_16x16x32_bf16 v[208:211], v[118:121], v[182:185], v[208:211]
	v_mfma_f32_16x16x32_bf16 v[212:215], v[118:121], v[198:201], v[212:215]
	v_mfma_f32_16x16x32_bf16 v[208:211], v[122:125], v[186:189], v[208:211]
	v_mfma_f32_16x16x32_bf16 v[212:215], v[122:125], v[202:205], v[212:215]
	s_waitcnt vmcnt(8)
	v_mfma_f32_16x16x32_bf16 v[216:219], v[126:129], v[174:177], 0
	v_mfma_f32_16x16x32_bf16 v[220:223], v[126:129], v[190:193], 0
	v_mfma_f32_16x16x32_bf16 v[216:219], v[130:133], v[178:181], v[216:219]
	v_mfma_f32_16x16x32_bf16 v[220:223], v[130:133], v[194:197], v[220:223]
	v_mfma_f32_16x16x32_bf16 v[216:219], v[134:137], v[182:185], v[216:219]
	v_mfma_f32_16x16x32_bf16 v[220:223], v[134:137], v[198:201], v[220:223]
	v_mfma_f32_16x16x32_bf16 v[216:219], v[138:141], v[186:189], v[216:219]
	v_mfma_f32_16x16x32_bf16 v[220:223], v[138:141], v[202:205], v[220:223]
	s_waitcnt vmcnt(4)
	v_mfma_f32_16x16x32_bf16 v[224:227], v[142:145], v[174:177], 0
	v_mfma_f32_16x16x32_bf16 v[228:231], v[142:145], v[190:193], 0
	v_mfma_f32_16x16x32_bf16 v[224:227], v[146:149], v[178:181], v[224:227]
	v_mfma_f32_16x16x32_bf16 v[228:231], v[146:149], v[194:197], v[228:231]
	v_mfma_f32_16x16x32_bf16 v[224:227], v[150:153], v[182:185], v[224:227]
	v_mfma_f32_16x16x32_bf16 v[228:231], v[150:153], v[198:201], v[228:231]
	v_mfma_f32_16x16x32_bf16 v[224:227], v[154:157], v[186:189], v[224:227]
	v_mfma_f32_16x16x32_bf16 v[228:231], v[154:157], v[202:205], v[228:231]
	s_waitcnt vmcnt(0)
	v_mfma_f32_16x16x32_bf16 v[232:235], v[158:161], v[174:177], 0
	v_mfma_f32_16x16x32_bf16 v[236:239], v[158:161], v[190:193], 0
	v_mfma_f32_16x16x32_bf16 v[232:235], v[162:165], v[178:181], v[232:235]
	v_mfma_f32_16x16x32_bf16 v[236:239], v[162:165], v[194:197], v[236:239]
	v_mfma_f32_16x16x32_bf16 v[232:235], v[166:169], v[182:185], v[232:235]
	v_mfma_f32_16x16x32_bf16 v[236:239], v[166:169], v[198:201], v[236:239]
	v_mfma_f32_16x16x32_bf16 v[232:235], v[170:173], v[186:189], v[232:235]
	v_mfma_f32_16x16x32_bf16 v[236:239], v[170:173], v[202:205], v[236:239]
	v_add_u32_e32 v52, s9, v57
	v_ashrrev_i32_e32 v53, 31, v52
	v_lshlrev_b64 v[64:65], 7, v[52:53]
	v_or_b32_e32 v54, 1, v52
	v_ashrrev_i32_e32 v55, 31, v54
	v_lshl_add_u64 v[0:1], v[52:53], 2, s[6:7]
	ds_write_b128 v34, v[208:211]
	ds_write_b128 v34, v[212:215] offset:1024
	ds_write_b128 v34, v[216:219] offset:2048
	ds_write_b128 v34, v[220:223] offset:3072
	ds_write_b128 v34, v[224:227] offset:4096
	ds_write_b128 v34, v[228:231] offset:5120
	ds_write_b128 v34, v[232:235] offset:6144
	ds_write_b128 v34, v[236:239] offset:7168
	s_waitcnt lgkmcnt(0)
	s_barrier
; __device__ __forceinline__ float softplus_f(float v) { return fmaxf(v, 0.f) + log1pf(expf(-fabsf(v))); }
;     __device__ __forceinline__ int lane_() const { return hw_lane(); }
; __device__ __forceinline__ void p1b_dt(Frame& F, const Ptrs& P) {
;     ...
;         __syncthreads();
;         f32x4 acc = part[(0 * 8 + rt * 2 + ct) * 64 + lane_];
; #pragma unroll
;         for (int w2 = 1; w2 < 8; ++w2) acc += part[(w2 * 8 + rt * 2 + ct) * 64 + lane_];
;         const int col = ct * 16 + fr; const float bias = col < 16 ? P.dtb_f[col] : P.dtb_b[col - 16];
; #pragma unroll
;         for (int i = 0; i < 4; ++i) { const int row = blk * 64 + rt * 16 + fq * 4 + i;
;             __hip_atomic_store(&DT[(size_t)row * 32 + col], softplus_f(acc[i] * RS[row] + bias), __ATOMIC_RELAXED, __HIP_MEMORY_SCOPE_AGENT); }
	global_load_dword v62, v[48:49], off
	global_load_dword v51, v[0:1], off
	global_load_dword v106, v[0:1], off offset:4
	global_load_dword v107, v[0:1], off offset:8
	global_load_dword v108, v[0:1], off offset:12
	ds_read_b128 v[0:3], v58
	ds_read_b128 v[4:7], v58 offset:8192
	ds_read_b128 v[8:11], v58 offset:16384
	ds_read_b128 v[12:15], v58 offset:24576
	ds_read_b128 v[16:19], v58 offset:32768
	ds_read_b128 v[20:23], v58 offset:40960
	ds_read_b128 v[24:27], v58 offset:49152
	ds_read_b128 v[28:31], v58 offset:57344
	s_waitcnt lgkmcnt(6)
	v_pk_add_f32 v[0:1], v[0:1], v[4:5]
	v_pk_add_f32 v[2:3], v[2:3], v[6:7]
	s_waitcnt lgkmcnt(5)
	v_pk_add_f32 v[0:1], v[0:1], v[8:9]
	v_pk_add_f32 v[2:3], v[2:3], v[10:11]
	s_waitcnt lgkmcnt(4)
	v_pk_add_f32 v[0:1], v[0:1], v[12:13]
	v_pk_add_f32 v[2:3], v[2:3], v[14:15]
	s_waitcnt lgkmcnt(3)
	v_pk_add_f32 v[0:1], v[0:1], v[16:17]
	v_pk_add_f32 v[2:3], v[2:3], v[18:19]
	s_waitcnt lgkmcnt(2)
	v_pk_add_f32 v[0:1], v[0:1], v[20:21]
	v_pk_add_f32 v[2:3], v[2:3], v[22:23]
	s_waitcnt lgkmcnt(1)
	v_pk_add_f32 v[0:1], v[0:1], v[24:25]
	v_pk_add_f32 v[2:3], v[2:3], v[26:27]
	s_waitcnt lgkmcnt(0)
	v_pk_add_f32 v[4:5], v[0:1], v[28:29]
	v_pk_add_f32 v[2:3], v[2:3], v[30:31]
	s_waitcnt vmcnt(0)
	v_fma_f32 v4, v4, v51, v62
	v_mul_f32_e64 v0, |v4|, s12
	v_fma_f32 v1, |v4|, s12, -v0
	v_rndne_f32_e32 v8, v0
	v_fma_f32 v1, |v4|, s17, v1
	v_sub_f32_e32 v0, v0, v8
	v_add_f32_e32 v0, v0, v1
	v_cvt_i32_f32_e32 v12, v8
	v_exp_f32_e32 v13, v0
	v_cmp_ngt_f32_e64 vcc, |v4|, s20
	v_max_f32_e32 v53, 0, v4
	v_lshl_add_u64 v[0:1], v[38:39], 0, v[64:65]
	v_ldexp_f32 v12, v13, v12
	v_cndmask_b32_e32 v12, 0, v12, vcc
	v_cmp_nlt_f32_e64 vcc, |v4|, s21
	v_lshl_add_u64 v[8:9], v[54:55], 2, s[6:7]
	s_nop 0
	v_cndmask_b32_e32 v4, v59, v12, vcc
	v_add_f32_e32 v16, 1.0, v4
	v_add_f32_e32 v17, -1.0, v16
	v_frexp_mant_f32_e32 v20, v16
	v_cvt_f64_f32_e32 v[12:13], v16
	v_sub_f32_e32 v21, v17, v16
	v_frexp_exp_i32_f64_e32 v12, v[12:13]
	v_cmp_gt_f32_e32 vcc, s23, v20
	v_sub_f32_e32 v17, v4, v17
	v_add_f32_e32 v13, 1.0, v21
	v_subbrev_co_u32_e32 v12, vcc, 0, v12, vcc
	v_add_f32_e32 v13, v17, v13
	v_sub_u32_e32 v17, 0, v12
	v_ldexp_f32 v16, v16, v17
	v_add_f32_e32 v20, -1.0, v16
	v_add_f32_e32 v21, 1.0, v16
	v_ldexp_f32 v13, v13, v17
	v_add_f32_e32 v17, 1.0, v20
	v_add_f32_e32 v24, -1.0, v21
	v_sub_f32_e32 v17, v16, v17
	v_sub_f32_e32 v16, v16, v24
	v_add_f32_e32 v24, v13, v17
	v_add_f32_e32 v13, v13, v16
	v_add_f32_e32 v28, v21, v13
	v_rcp_f32_e32 v29, v28
	v_add_f32_e32 v17, v20, v24
	v_sub_f32_e32 v20, v20, v17
	v_sub_f32_e32 v16, v21, v28
	v_mul_f32_e32 v63, v17, v29
	v_add_f32_e32 v51, v24, v20
	v_mul_f32_e32 v20, v28, v63
	v_add_f32_e32 v13, v13, v16
	v_fma_f32 v24, v63, v28, -v20
	v_fmac_f32_e32 v24, v63, v13
	v_add_f32_e32 v16, v20, v24
	v_sub_f32_e32 v21, v17, v16
	v_mov_b32_e32 v25, v16
	v_pk_add_f32 v[16:17], v[16:17], v[20:21] neg_lo:[0,1] neg_hi:[0,1]
	v_cvt_f32_i32_e32 v12, v12
	v_pk_add_f32 v[16:17], v[16:17], v[24:25] neg_lo:[0,1] neg_hi:[0,1]
	v_cmp_neq_f32_e32 vcc, s22, v4
	v_add_f32_e32 v17, v51, v17
	v_add_f32_e32 v16, v16, v17
	v_add_f32_e32 v17, v21, v16
	v_mul_f32_e32 v25, v29, v17
	v_mul_f32_e32 v20, v28, v25
	v_sub_f32_e32 v21, v21, v17
	v_add_f32_e32 v64, v63, v25
	v_fma_f32 v24, v25, v28, -v20
	v_add_f32_e32 v51, v16, v21
	v_sub_f32_e32 v16, v64, v63
	v_fmac_f32_e32 v24, v25, v13
	v_sub_f32_e32 v13, v25, v16
	v_add_f32_e32 v16, v20, v24
	v_sub_f32_e32 v21, v17, v16
	v_mov_b32_e32 v25, v16
	v_pk_add_f32 v[16:17], v[16:17], v[20:21] neg_lo:[0,1] neg_hi:[0,1]
	s_nop 0
	v_pk_add_f32 v[16:17], v[16:17], v[24:25] neg_lo:[0,1] neg_hi:[0,1]
	s_nop 0
	v_add_f32_e32 v17, v51, v17
	v_add_f32_e32 v16, v16, v17
	v_add_f32_e32 v16, v21, v16
	v_mul_f32_e32 v16, v29, v16
	v_add_f32_e32 v13, v13, v16
	v_add_f32_e32 v16, v64, v13
	v_mul_f32_e32 v20, v16, v16
	v_sub_f32_e32 v21, v16, v64
	v_fmamk_f32 v24, v20, 0x3e9b6dac, v60
	v_sub_f32_e32 v21, v13, v21
	v_mul_f32_e32 v13, v16, v20
	v_fmaak_f32 v51, v20, v24, 0x3f2aaada
	v_ldexp_f32 v25, v21, 1
	v_pk_mul_f32 v[20:21], v[12:13], v[50:51]
	v_ldexp_f32 v17, v16, 1
	v_fma_f32 v16, v12, s28, -v20
	v_fmac_f32_e32 v16, 0xb102e308, v12
	v_pk_add_f32 v[12:13], v[20:21], v[16:17]
	v_mov_b32_e32 v24, v20
	v_sub_f32_e32 v51, v13, v17
	v_pk_add_f32 v[28:29], v[12:13], v[20:21] neg_lo:[0,1] neg_hi:[0,1]
	v_sub_f32_e32 v20, v21, v51
	v_add_f32_e32 v25, v25, v20
	v_pk_add_f32 v[20:21], v[12:13], v[24:25]
	v_mov_b32_e32 v17, v12
	v_mov_b32_e32 v29, v21
	v_pk_add_f32 v[66:67], v[16:17], v[28:29] neg_lo:[0,1] neg_hi:[0,1]
	v_pk_add_f32 v[16:17], v[16:17], v[28:29]
	v_mov_b32_e32 v65, v12
	v_pk_add_f32 v[28:29], v[16:17], v[12:13] op_sel:[1,0] op_sel_hi:[0,1] neg_lo:[0,1] neg_hi:[0,1]
	v_mov_b32_e32 v64, v25
	v_mov_b32_e32 v24, v21
	v_mov_b32_e32 v25, v17
	v_pk_mov_b32 v[12:13], v[12:13], v[28:29] op_sel:[1,0]
	v_pk_add_f32 v[20:21], v[20:21], v[28:29] op_sel_hi:[1,0] neg_lo:[0,1] neg_hi:[0,1]
	v_pk_add_f32 v[12:13], v[24:25], v[12:13] neg_lo:[0,1] neg_hi:[0,1]
	v_mov_b32_e32 v20, v66
	v_pk_add_f32 v[12:13], v[64:65], v[12:13] neg_lo:[0,1] neg_hi:[0,1]
	v_mov_b32_e32 v67, v17
	v_pk_add_f32 v[20:21], v[20:21], v[12:13]
	s_nop 0
	v_pk_add_f32 v[24:25], v[20:21], v[20:21] op_sel:[0,1] op_sel_hi:[1,0]
	s_nop 0
	v_pk_add_f32 v[16:17], v[16:17], v[24:25] op_sel:[1,0] op_sel_hi:[0,1]
	v_mov_b32_e32 v21, v16
	v_mov_b32_e32 v13, v24
	v_pk_add_f32 v[24:25], v[20:21], v[66:67] neg_lo:[0,1] neg_hi:[0,1]
	s_nop 0
	v_sub_f32_e32 v17, v20, v24
	v_pk_add_f32 v[12:13], v[12:13], v[24:25] neg_lo:[0,1] neg_hi:[0,1]
	v_sub_f32_e32 v17, v66, v17
	v_add_f32_e32 v12, v12, v17
	v_add_f32_e32 v12, v12, v13
	v_add_f32_e32 v12, v16, v12
; __device__ __forceinline__ float softplus_f(float v) { return fmaxf(v, 0.f) + log1pf(expf(-fabsf(v))); }
; __device__ __forceinline__ void p1b_dt(Frame& F, const Ptrs& P) {
;     ...
;         const int col = ct * 16 + fr; const float bias = col < 16 ? P.dtb_f[col] : P.dtb_b[col - 16];
; #pragma unroll
;         for (int i = 0; i < 4; ++i) { const int row = blk * 64 + rt * 16 + fq * 4 + i;
;             __hip_atomic_store(&DT[(size_t)row * 32 + col], softplus_f(acc[i] * RS[row] + bias), __ATOMIC_RELAXED, __HIP_MEMORY_SCOPE_AGENT); }
	v_cndmask_b32_e32 v12, v59, v12, vcc
	v_cmp_lt_f32_e64 vcc, |v4|, s29
	s_nop 1
	v_cndmask_b32_e32 v4, v12, v4, vcc
	v_add_f32_e32 v4, v53, v4
	global_store_dword v[0:1], v4, off sc1
	v_mov_b32_e32 v4, v106
	v_lshlrev_b64 v[8:9], 7, v[54:55]
	v_or_b32_e32 v0, 2, v52
	v_ashrrev_i32_e32 v1, 31, v0
	v_lshl_add_u64 v[8:9], v[38:39], 0, v[8:9]
	s_nop 0
	v_fma_f32 v12, v5, v4, v62
	v_mul_f32_e64 v4, |v12|, s12
	v_fma_f32 v5, |v12|, s12, -v4
	v_rndne_f32_e32 v13, v4
	v_fma_f32 v5, |v12|, s17, v5
	v_sub_f32_e32 v4, v4, v13
	v_add_f32_e32 v4, v4, v5
	v_cvt_i32_f32_e32 v13, v13
	v_exp_f32_e32 v16, v4
	v_cmp_ngt_f32_e64 vcc, |v12|, s20
	v_max_f32_e32 v53, 0, v12
	v_lshl_add_u64 v[4:5], v[0:1], 2, s[6:7]
	v_ldexp_f32 v13, v16, v13
	v_cndmask_b32_e32 v13, 0, v13, vcc
	v_cmp_nlt_f32_e64 vcc, |v12|, s21
	v_lshlrev_b64 v[0:1], 7, v[0:1]
	v_lshl_add_u64 v[0:1], v[38:39], 0, v[0:1]
	v_cndmask_b32_e32 v63, v59, v13, vcc
	v_add_f32_e32 v16, 1.0, v63
	v_add_f32_e32 v17, -1.0, v16
	v_frexp_mant_f32_e32 v20, v16
	v_cvt_f64_f32_e32 v[12:13], v16
	v_sub_f32_e32 v21, v17, v16
	v_frexp_exp_i32_f64_e32 v12, v[12:13]
	v_cmp_gt_f32_e32 vcc, s23, v20
	v_sub_f32_e32 v17, v63, v17
	v_add_f32_e32 v13, 1.0, v21
	v_subbrev_co_u32_e32 v12, vcc, 0, v12, vcc
	v_add_f32_e32 v13, v17, v13
	v_sub_u32_e32 v17, 0, v12
	v_ldexp_f32 v16, v16, v17
	v_add_f32_e32 v20, -1.0, v16
	v_add_f32_e32 v21, 1.0, v16
	v_ldexp_f32 v13, v13, v17
	v_add_f32_e32 v17, 1.0, v20
	v_add_f32_e32 v24, -1.0, v21
	v_sub_f32_e32 v17, v16, v17
	v_sub_f32_e32 v16, v16, v24
	v_add_f32_e32 v24, v13, v17
	v_add_f32_e32 v13, v13, v16
	v_add_f32_e32 v28, v21, v13
	v_rcp_f32_e32 v29, v28
	v_add_f32_e32 v17, v20, v24
	v_sub_f32_e32 v20, v20, v17
	v_sub_f32_e32 v16, v21, v28
	v_mul_f32_e32 v54, v17, v29
	v_add_f32_e32 v51, v24, v20
	v_mul_f32_e32 v20, v28, v54
	v_add_f32_e32 v13, v13, v16
	v_fma_f32 v24, v54, v28, -v20
	v_fmac_f32_e32 v24, v54, v13
	v_add_f32_e32 v16, v20, v24
	v_sub_f32_e32 v21, v17, v16
	v_mov_b32_e32 v25, v16
	v_pk_add_f32 v[16:17], v[16:17], v[20:21] neg_lo:[0,1] neg_hi:[0,1]
	v_cvt_f32_i32_e32 v12, v12
	v_pk_add_f32 v[16:17], v[16:17], v[24:25] neg_lo:[0,1] neg_hi:[0,1]
	v_cmp_neq_f32_e32 vcc, s22, v63
	v_add_f32_e32 v17, v51, v17
	v_add_f32_e32 v16, v16, v17
	v_add_f32_e32 v17, v21, v16
	v_mul_f32_e32 v25, v29, v17
	v_mul_f32_e32 v20, v28, v25
	v_sub_f32_e32 v21, v21, v17
	v_add_f32_e32 v55, v54, v25
	v_fma_f32 v24, v25, v28, -v20
	v_add_f32_e32 v51, v16, v21
	v_sub_f32_e32 v16, v55, v54
	v_fmac_f32_e32 v24, v25, v13
	v_sub_f32_e32 v13, v25, v16
	v_add_f32_e32 v16, v20, v24
	v_sub_f32_e32 v21, v17, v16
	v_mov_b32_e32 v25, v16
	v_pk_add_f32 v[16:17], v[16:17], v[20:21] neg_lo:[0,1] neg_hi:[0,1]
	s_nop 0
	v_pk_add_f32 v[16:17], v[16:17], v[24:25] neg_lo:[0,1] neg_hi:[0,1]
	s_nop 0
	v_add_f32_e32 v17, v51, v17
	v_add_f32_e32 v16, v16, v17
	v_add_f32_e32 v16, v21, v16
	v_mul_f32_e32 v16, v29, v16
	v_add_f32_e32 v13, v13, v16
	v_add_f32_e32 v16, v55, v13
	v_mul_f32_e32 v20, v16, v16
	v_sub_f32_e32 v21, v16, v55
	v_fmamk_f32 v24, v20, 0x3e9b6dac, v60
	v_sub_f32_e32 v21, v13, v21
	v_mul_f32_e32 v13, v16, v20
	v_fmaak_f32 v51, v20, v24, 0x3f2aaada
	v_ldexp_f32 v25, v21, 1
	v_pk_mul_f32 v[20:21], v[12:13], v[50:51]
	v_ldexp_f32 v17, v16, 1
	v_fma_f32 v16, v12, s28, -v20
	v_fmac_f32_e32 v16, 0xb102e308, v12
	v_pk_add_f32 v[12:13], v[20:21], v[16:17]
	v_mov_b32_e32 v24, v20
	v_sub_f32_e32 v51, v13, v17
	v_pk_add_f32 v[28:29], v[12:13], v[20:21] neg_lo:[0,1] neg_hi:[0,1]
	v_sub_f32_e32 v20, v21, v51
	v_add_f32_e32 v25, v25, v20
	v_pk_add_f32 v[20:21], v[12:13], v[24:25]
	v_mov_b32_e32 v17, v12
	v_mov_b32_e32 v29, v21
	v_pk_add_f32 v[64:65], v[16:17], v[28:29] neg_lo:[0,1] neg_hi:[0,1]
	v_pk_add_f32 v[16:17], v[16:17], v[28:29]
	v_mov_b32_e32 v55, v12
	v_pk_add_f32 v[28:29], v[16:17], v[12:13] op_sel:[1,0] op_sel_hi:[0,1] neg_lo:[0,1] neg_hi:[0,1]
	v_mov_b32_e32 v54, v25
	v_mov_b32_e32 v24, v21
	v_mov_b32_e32 v25, v17
	v_pk_mov_b32 v[12:13], v[12:13], v[28:29] op_sel:[1,0]
	v_pk_add_f32 v[20:21], v[20:21], v[28:29] op_sel_hi:[1,0] neg_lo:[0,1] neg_hi:[0,1]
	v_pk_add_f32 v[12:13], v[24:25], v[12:13] neg_lo:[0,1] neg_hi:[0,1]
	v_mov_b32_e32 v20, v64
	v_pk_add_f32 v[12:13], v[54:55], v[12:13] neg_lo:[0,1] neg_hi:[0,1]
	v_mov_b32_e32 v65, v17
	v_pk_add_f32 v[20:21], v[20:21], v[12:13]
	s_nop 0
	v_pk_add_f32 v[24:25], v[20:21], v[20:21] op_sel:[0,1] op_sel_hi:[1,0]
	s_nop 0
	v_pk_add_f32 v[16:17], v[16:17], v[24:25] op_sel:[1,0] op_sel_hi:[0,1]
	v_mov_b32_e32 v21, v16
	v_mov_b32_e32 v13, v24
	v_pk_add_f32 v[24:25], v[20:21], v[64:65] neg_lo:[0,1] neg_hi:[0,1]
	s_nop 0
	v_sub_f32_e32 v17, v20, v24
	v_pk_add_f32 v[12:13], v[12:13], v[24:25] neg_lo:[0,1] neg_hi:[0,1]
	v_sub_f32_e32 v17, v64, v17
	v_add_f32_e32 v12, v12, v17
	v_add_f32_e32 v12, v12, v13
	v_add_f32_e32 v12, v16, v12
	v_cndmask_b32_e32 v12, v59, v12, vcc
	v_cmp_lt_f32_e64 vcc, |v63|, s29
	s_nop 1
	v_cndmask_b32_e32 v12, v12, v63, vcc
	v_add_f32_e32 v12, v53, v12
	global_store_dword v[8:9], v12, off sc1
	v_mov_b32_e32 v8, v107
	v_or_b32_e32 v4, 3, v52
	v_ashrrev_i32_e32 v5, 31, v4
	s_nop 0
	v_fma_f32 v2, v2, v8, v62
	v_mul_f32_e64 v6, |v2|, s12
	v_fma_f32 v7, |v2|, s12, -v6
	v_rndne_f32_e32 v8, v6
	v_fma_f32 v7, |v2|, s17, v7
	v_sub_f32_e32 v6, v6, v8
	v_add_f32_e32 v6, v6, v7
	v_cvt_i32_f32_e32 v8, v8
	v_exp_f32_e32 v9, v6
	v_cmp_ngt_f32_e64 vcc, |v2|, s20
	v_max_f32_e32 v22, 0, v2
	v_lshl_add_u64 v[6:7], v[4:5], 2, s[6:7]
	v_ldexp_f32 v8, v9, v8
	v_cndmask_b32_e32 v8, 0, v8, vcc
	v_cmp_nlt_f32_e64 vcc, |v2|, s21
	s_nop 1
	v_cndmask_b32_e32 v2, v59, v8, vcc
	v_add_f32_e32 v10, 1.0, v2
	v_add_f32_e32 v11, -1.0, v10
	v_frexp_mant_f32_e32 v12, v10
; __device__ __forceinline__ float softplus_f(float v) { return fmaxf(v, 0.f) + log1pf(expf(-fabsf(v))); }
; __device__ __forceinline__ void p1b_dt(Frame& F, const Ptrs& P) {
;     ...
;         const int col = ct * 16 + fr; const float bias = col < 16 ? P.dtb_f[col] : P.dtb_b[col - 16];
; #pragma unroll
;         for (int i = 0; i < 4; ++i) { const int row = blk * 64 + rt * 16 + fq * 4 + i;
;             __hip_atomic_store(&DT[(size_t)row * 32 + col], softplus_f(acc[i] * RS[row] + bias), __ATOMIC_RELAXED, __HIP_MEMORY_SCOPE_AGENT); }
	v_cvt_f64_f32_e32 v[8:9], v10
	v_sub_f32_e32 v13, v11, v10
	v_frexp_exp_i32_f64_e32 v8, v[8:9]
	v_cmp_gt_f32_e32 vcc, s23, v12
	v_sub_f32_e32 v11, v2, v11
	v_add_f32_e32 v9, 1.0, v13
	v_subbrev_co_u32_e32 v8, vcc, 0, v8, vcc
	v_add_f32_e32 v9, v11, v9
	v_sub_u32_e32 v11, 0, v8
	v_ldexp_f32 v10, v10, v11
	v_add_f32_e32 v12, -1.0, v10
	v_add_f32_e32 v13, 1.0, v10
	v_ldexp_f32 v9, v9, v11
	v_add_f32_e32 v11, 1.0, v12
	v_add_f32_e32 v14, -1.0, v13
	v_sub_f32_e32 v11, v10, v11
	v_sub_f32_e32 v10, v10, v14
	v_add_f32_e32 v14, v9, v11
	v_add_f32_e32 v9, v9, v10
	v_add_f32_e32 v16, v13, v9
	v_rcp_f32_e32 v17, v16
	v_add_f32_e32 v11, v12, v14
	v_sub_f32_e32 v12, v12, v11
	v_sub_f32_e32 v10, v13, v16
	v_mul_f32_e32 v19, v11, v17
	v_add_f32_e32 v18, v14, v12
	v_mul_f32_e32 v12, v16, v19
	v_add_f32_e32 v9, v9, v10
	v_fma_f32 v14, v19, v16, -v12
	v_fmac_f32_e32 v14, v19, v9
	v_add_f32_e32 v10, v12, v14
	v_sub_f32_e32 v13, v11, v10
	v_mov_b32_e32 v15, v10
	v_pk_add_f32 v[10:11], v[10:11], v[12:13] neg_lo:[0,1] neg_hi:[0,1]
	v_cvt_f32_i32_e32 v8, v8
	v_pk_add_f32 v[10:11], v[10:11], v[14:15] neg_lo:[0,1] neg_hi:[0,1]
	v_cmp_neq_f32_e32 vcc, s22, v2
	v_add_f32_e32 v11, v18, v11
	v_add_f32_e32 v10, v10, v11
	v_add_f32_e32 v11, v13, v10
	v_mul_f32_e32 v15, v17, v11
	v_mul_f32_e32 v12, v16, v15
	v_sub_f32_e32 v13, v13, v11
	v_add_f32_e32 v20, v19, v15
	v_fma_f32 v14, v15, v16, -v12
	v_add_f32_e32 v18, v10, v13
	v_sub_f32_e32 v10, v20, v19
	v_fmac_f32_e32 v14, v15, v9
	v_sub_f32_e32 v9, v15, v10
	v_add_f32_e32 v10, v12, v14
	v_sub_f32_e32 v13, v11, v10
	v_mov_b32_e32 v15, v10
	v_pk_add_f32 v[10:11], v[10:11], v[12:13] neg_lo:[0,1] neg_hi:[0,1]
	s_nop 0
	v_pk_add_f32 v[10:11], v[10:11], v[14:15] neg_lo:[0,1] neg_hi:[0,1]
	s_nop 0
	v_add_f32_e32 v11, v18, v11
	v_add_f32_e32 v10, v10, v11
	v_add_f32_e32 v10, v13, v10
	v_mul_f32_e32 v10, v17, v10
	v_add_f32_e32 v9, v9, v10
	v_add_f32_e32 v10, v20, v9
	v_mul_f32_e32 v12, v10, v10
	v_sub_f32_e32 v13, v10, v20
	v_fmamk_f32 v14, v12, 0x3e9b6dac, v60
	v_sub_f32_e32 v13, v9, v13
	v_mul_f32_e32 v9, v10, v12
	v_fmaak_f32 v51, v12, v14, 0x3f2aaada
	v_ldexp_f32 v15, v13, 1
	v_pk_mul_f32 v[12:13], v[8:9], v[50:51]
	v_ldexp_f32 v11, v10, 1
	v_fma_f32 v10, v8, s28, -v12
	v_fmac_f32_e32 v10, 0xb102e308, v8
	v_pk_add_f32 v[8:9], v[12:13], v[10:11]
	v_mov_b32_e32 v14, v12
	v_sub_f32_e32 v18, v9, v11
	v_pk_add_f32 v[16:17], v[8:9], v[12:13] neg_lo:[0,1] neg_hi:[0,1]
	v_sub_f32_e32 v12, v13, v18
	v_add_f32_e32 v15, v15, v12
	v_pk_add_f32 v[12:13], v[8:9], v[14:15]
	v_mov_b32_e32 v11, v8
	v_mov_b32_e32 v17, v13
	v_pk_add_f32 v[20:21], v[10:11], v[16:17] neg_lo:[0,1] neg_hi:[0,1]
	v_pk_add_f32 v[10:11], v[10:11], v[16:17]
	v_mov_b32_e32 v19, v8
	v_pk_add_f32 v[16:17], v[10:11], v[8:9] op_sel:[1,0] op_sel_hi:[0,1] neg_lo:[0,1] neg_hi:[0,1]
	v_mov_b32_e32 v18, v15
	v_mov_b32_e32 v14, v13
	v_mov_b32_e32 v15, v11
	v_pk_mov_b32 v[8:9], v[8:9], v[16:17] op_sel:[1,0]
	v_pk_add_f32 v[12:13], v[12:13], v[16:17] op_sel_hi:[1,0] neg_lo:[0,1] neg_hi:[0,1]
	v_pk_add_f32 v[8:9], v[14:15], v[8:9] neg_lo:[0,1] neg_hi:[0,1]
	v_mov_b32_e32 v12, v20
	v_pk_add_f32 v[8:9], v[18:19], v[8:9] neg_lo:[0,1] neg_hi:[0,1]
	v_mov_b32_e32 v21, v11
	v_pk_add_f32 v[12:13], v[12:13], v[8:9]
	s_nop 0
	v_pk_add_f32 v[14:15], v[12:13], v[12:13] op_sel:[0,1] op_sel_hi:[1,0]
	s_nop 0
	v_pk_add_f32 v[10:11], v[10:11], v[14:15] op_sel:[1,0] op_sel_hi:[0,1]
	v_mov_b32_e32 v13, v10
	v_mov_b32_e32 v9, v14
	v_pk_add_f32 v[14:15], v[12:13], v[20:21] neg_lo:[0,1] neg_hi:[0,1]
	s_nop 0
	v_sub_f32_e32 v11, v12, v14
	v_pk_add_f32 v[8:9], v[8:9], v[14:15] neg_lo:[0,1] neg_hi:[0,1]
	v_sub_f32_e32 v11, v20, v11
	v_add_f32_e32 v8, v8, v11
	v_add_f32_e32 v8, v8, v9
	v_add_f32_e32 v8, v10, v8
	v_cndmask_b32_e32 v8, v59, v8, vcc
	v_cmp_lt_f32_e64 vcc, |v2|, s29
	s_nop 1
	v_cndmask_b32_e32 v2, v8, v2, vcc
	v_add_f32_e32 v2, v22, v2
	global_store_dword v[0:1], v2, off sc1
	v_mov_b32_e32 v0, v108
	s_nop 0
	v_fmac_f32_e32 v62, v3, v0
	v_mul_f32_e64 v0, |v62|, s12
	v_fma_f32 v1, |v62|, s12, -v0
	v_rndne_f32_e32 v2, v0
	v_fma_f32 v1, |v62|, s17, v1
	v_sub_f32_e32 v0, v0, v2
	v_add_f32_e32 v0, v0, v1
	v_cvt_i32_f32_e32 v2, v2
	v_exp_f32_e32 v3, v0
	v_cmp_ngt_f32_e64 vcc, |v62|, s20
	v_lshlrev_b64 v[0:1], 7, v[4:5]
; __device__ __forceinline__ float softplus_f(float v) { return fmaxf(v, 0.f) + log1pf(expf(-fabsf(v))); }
;     __device__ __forceinline__ int lane_() const { return hw_lane(); }
; __device__ __forceinline__ void p1b_dt(Frame& F, const Ptrs& P) {
;     ...
;         for (int i = 0; i < 4; ++i) { const int row = blk * 64 + rt * 16 + fq * 4 + i;
;             __hip_atomic_store(&DT[(size_t)row * 32 + col], softplus_f(acc[i] * RS[row] + bias), __ATOMIC_RELAXED, __HIP_MEMORY_SCOPE_AGENT); }
;         asm volatile("s_waitcnt vmcnt(0)" ::: "memory");
;         __syncthreads();
;         if (w == 0 && lane_ == 0) __hip_atomic_store((unsigned*)(P.ws + WS_CTL) + CW_DTF + blk, 1u, __ATOMIC_RELAXED, __HIP_MEMORY_SCOPE_AGENT);
	v_max_f32_e32 v16, 0, v62
	v_ldexp_f32 v2, v3, v2
	v_cndmask_b32_e32 v2, 0, v2, vcc
	v_cmp_nlt_f32_e64 vcc, |v62|, s21
	v_lshl_add_u64 v[0:1], v[38:39], 0, v[0:1]
	s_nop 0
	v_cndmask_b32_e32 v17, v59, v2, vcc
	v_add_f32_e32 v4, 1.0, v17
	v_add_f32_e32 v5, -1.0, v4
	v_frexp_mant_f32_e32 v6, v4
	v_cvt_f64_f32_e32 v[2:3], v4
	v_sub_f32_e32 v7, v5, v4
	v_frexp_exp_i32_f64_e32 v2, v[2:3]
	v_cmp_gt_f32_e32 vcc, s23, v6
	v_sub_f32_e32 v5, v17, v5
	v_add_f32_e32 v3, 1.0, v7
	v_subbrev_co_u32_e32 v2, vcc, 0, v2, vcc
	v_add_f32_e32 v3, v5, v3
	v_sub_u32_e32 v5, 0, v2
	v_ldexp_f32 v4, v4, v5
	v_add_f32_e32 v6, -1.0, v4
	v_add_f32_e32 v7, 1.0, v4
	v_ldexp_f32 v3, v3, v5
	v_add_f32_e32 v5, 1.0, v6
	v_add_f32_e32 v8, -1.0, v7
	v_sub_f32_e32 v5, v4, v5
	v_sub_f32_e32 v4, v4, v8
	v_add_f32_e32 v8, v3, v5
	v_add_f32_e32 v3, v3, v4
	v_add_f32_e32 v10, v7, v3
	v_rcp_f32_e32 v11, v10
	v_add_f32_e32 v5, v6, v8
	v_sub_f32_e32 v6, v6, v5
	v_sub_f32_e32 v4, v7, v10
	v_mul_f32_e32 v13, v5, v11
	v_add_f32_e32 v12, v8, v6
	v_mul_f32_e32 v6, v10, v13
	v_add_f32_e32 v3, v3, v4
	v_fma_f32 v8, v13, v10, -v6
	v_fmac_f32_e32 v8, v13, v3
	v_add_f32_e32 v4, v6, v8
	v_sub_f32_e32 v7, v5, v4
	v_mov_b32_e32 v9, v4
	v_pk_add_f32 v[4:5], v[4:5], v[6:7] neg_lo:[0,1] neg_hi:[0,1]
	v_cvt_f32_i32_e32 v2, v2
	v_pk_add_f32 v[4:5], v[4:5], v[8:9] neg_lo:[0,1] neg_hi:[0,1]
	v_cmp_neq_f32_e32 vcc, s22, v17
	v_add_f32_e32 v5, v12, v5
	v_add_f32_e32 v4, v4, v5
	v_add_f32_e32 v5, v7, v4
	v_mul_f32_e32 v9, v11, v5
	v_mul_f32_e32 v6, v10, v9
	v_sub_f32_e32 v7, v7, v5
	v_add_f32_e32 v14, v13, v9
	v_fma_f32 v8, v9, v10, -v6
	v_add_f32_e32 v12, v4, v7
	v_sub_f32_e32 v4, v14, v13
	v_fmac_f32_e32 v8, v9, v3
	v_sub_f32_e32 v3, v9, v4
	v_add_f32_e32 v4, v6, v8
	v_sub_f32_e32 v7, v5, v4
	v_mov_b32_e32 v9, v4
	v_pk_add_f32 v[4:5], v[4:5], v[6:7] neg_lo:[0,1] neg_hi:[0,1]
	s_nop 0
	v_pk_add_f32 v[4:5], v[4:5], v[8:9] neg_lo:[0,1] neg_hi:[0,1]
	s_nop 0
	v_add_f32_e32 v5, v12, v5
	v_add_f32_e32 v4, v4, v5
	v_add_f32_e32 v4, v7, v4
	v_mul_f32_e32 v4, v11, v4
	v_add_f32_e32 v3, v3, v4
	v_add_f32_e32 v4, v14, v3
	v_mul_f32_e32 v6, v4, v4
	v_sub_f32_e32 v7, v4, v14
	v_fmamk_f32 v8, v6, 0x3e9b6dac, v60
	v_sub_f32_e32 v7, v3, v7
	v_mul_f32_e32 v3, v4, v6
	v_fmaak_f32 v51, v6, v8, 0x3f2aaada
	v_ldexp_f32 v9, v7, 1
	v_pk_mul_f32 v[6:7], v[2:3], v[50:51]
	v_ldexp_f32 v5, v4, 1
	v_fma_f32 v4, v2, s28, -v6
	v_fmac_f32_e32 v4, 0xb102e308, v2
	v_pk_add_f32 v[2:3], v[6:7], v[4:5]
	v_mov_b32_e32 v8, v6
	v_sub_f32_e32 v12, v3, v5
	v_pk_add_f32 v[10:11], v[2:3], v[6:7] neg_lo:[0,1] neg_hi:[0,1]
	v_sub_f32_e32 v6, v7, v12
	v_add_f32_e32 v9, v9, v6
	v_pk_add_f32 v[6:7], v[2:3], v[8:9]
	v_mov_b32_e32 v5, v2
	v_mov_b32_e32 v11, v7
	v_pk_add_f32 v[14:15], v[4:5], v[10:11] neg_lo:[0,1] neg_hi:[0,1]
	v_pk_add_f32 v[4:5], v[4:5], v[10:11]
	v_mov_b32_e32 v13, v2
	v_pk_add_f32 v[10:11], v[4:5], v[2:3] op_sel:[1,0] op_sel_hi:[0,1] neg_lo:[0,1] neg_hi:[0,1]
	v_mov_b32_e32 v12, v9
	v_mov_b32_e32 v8, v7
	v_mov_b32_e32 v9, v5
	v_pk_mov_b32 v[2:3], v[2:3], v[10:11] op_sel:[1,0]
	v_pk_add_f32 v[6:7], v[6:7], v[10:11] op_sel_hi:[1,0] neg_lo:[0,1] neg_hi:[0,1]
	v_pk_add_f32 v[2:3], v[8:9], v[2:3] neg_lo:[0,1] neg_hi:[0,1]
	v_mov_b32_e32 v6, v14
	v_pk_add_f32 v[2:3], v[12:13], v[2:3] neg_lo:[0,1] neg_hi:[0,1]
	v_mov_b32_e32 v15, v5
	v_pk_add_f32 v[6:7], v[6:7], v[2:3]
	s_nop 0
	v_pk_add_f32 v[8:9], v[6:7], v[6:7] op_sel:[0,1] op_sel_hi:[1,0]
	s_nop 0
	v_pk_add_f32 v[4:5], v[4:5], v[8:9] op_sel:[1,0] op_sel_hi:[0,1]
	v_mov_b32_e32 v7, v4
	v_mov_b32_e32 v3, v8
	v_pk_add_f32 v[8:9], v[6:7], v[14:15] neg_lo:[0,1] neg_hi:[0,1]
	s_nop 0
	v_sub_f32_e32 v5, v6, v8
	v_pk_add_f32 v[2:3], v[2:3], v[8:9] neg_lo:[0,1] neg_hi:[0,1]
	v_sub_f32_e32 v5, v14, v5
	v_add_f32_e32 v2, v2, v5
	v_add_f32_e32 v2, v2, v3
	v_add_f32_e32 v2, v4, v2
	v_cndmask_b32_e32 v2, v59, v2, vcc
	v_cmp_lt_f32_e64 vcc, |v17|, s29
	s_nop 1
	v_cndmask_b32_e32 v2, v2, v17, vcc
	v_add_f32_e32 v2, v16, v2
	global_store_dword v[0:1], v2, off sc1
	s_waitcnt vmcnt(0)
	s_barrier
	s_and_saveexec_b64 s[10:11], s[2:3]
	s_cbranch_execz .LBB0_373
	s_ashr_i32 s9, s8, 31
	s_lshl_b64 s[8:9], s[8:9], 2
	s_add_u32 s8, s13, s8
	s_addc_u32 s9, s14, s9
	global_store_dword v35, v61, s[8:9] sc1
	s_branch .LBB0_373
